# v39 + ML-out weight conversion moved from the layer-0 up-proj window to the ML-in idle window (third pass)
# baseline (speedup 1.0000x reference)
.LBB0_160:
	s_cmp_eq_u32 s101, 1
	s_cbranch_scc1 .Lcv1_ret
	s_cmp_eq_u32 s101, 4
	s_cbranch_scc1 .Lcv_relay_ret3
	s_cmp_eq_u32 s101, 5
	s_cbranch_scc1 .Lcv_relay_ret3
	s_cmp_eq_u32 s101, 6
	s_cbranch_scc1 .Lcv_relay_ret3
	s_cmp_lg_u32 s101, 0
	s_cbranch_scc1 .Lcv_relay_ret
	s_mov_b64 s[76:77], s[88:89]
	v_and_b32_e32 v20, 63, v0
	s_cmpk_gt_i32 s2, 0x407f
	v_mbcnt_lo_u32_b32 v166, -1, 0
	s_mov_b32 s72, s86
	s_mov_b64 s[78:79], s[90:91]
	s_cbranch_scc1 .LBB0_165
	v_mbcnt_hi_u32_b32 v4, -1, v166
	v_and_b32_e32 v5, 64, v4
	v_add_u32_e32 v5, 64, v5
	v_xor_b32_e32 v6, 1, v4
	v_cmp_lt_i32_e32 vcc, v6, v5
	s_load_dwordx2 s[4:5], s[0:1], 0x48
	v_mov_b32_e32 v3, 0
	v_cndmask_b32_e32 v6, v4, v6, vcc
	v_lshlrev_b32_e32 v19, 2, v6
	v_xor_b32_e32 v6, 2, v4
	v_cmp_lt_i32_e32 vcc, v6, v5
	v_lshlrev_b32_e32 v2, 4, v20
	s_waitcnt lgkmcnt(0)
	v_lshl_add_u64 v[22:23], s[4:5], 0, v[2:3]
	v_cndmask_b32_e32 v6, v4, v6, vcc
	v_lshlrev_b32_e32 v32, 2, v6
	v_xor_b32_e32 v6, 4, v4
	v_cmp_lt_i32_e32 vcc, v6, v5
	s_mov_b64 s[4:5], 0x4200000
	v_lshl_add_u64 v[26:27], s[76:77], 0, v[2:3]
	v_cndmask_b32_e32 v6, v4, v6, vcc
	v_lshlrev_b32_e32 v33, 2, v6
	v_xor_b32_e32 v6, 8, v4
	v_cmp_lt_i32_e32 vcc, v6, v5
	v_lshlrev_b32_e32 v37, 4, v20
	v_mov_b32_e32 v38, 0x358637bd
	v_cndmask_b32_e32 v6, v4, v6, vcc
	v_lshlrev_b32_e32 v34, 2, v6
	v_xor_b32_e32 v6, 16, v4
	v_cmp_lt_i32_e32 vcc, v6, v5
	s_mov_b32 s3, 0xf800000
	v_mov_b32_e32 v39, 0x260
	v_cndmask_b32_e32 v6, v4, v6, vcc
	v_lshlrev_b32_e32 v35, 2, v6
	v_xor_b32_e32 v6, 32, v4
	v_cmp_lt_i32_e32 vcc, v6, v5
	v_mov_b32_e32 v5, v3
	s_nop 0
	v_cndmask_b32_e32 v4, v4, v6, vcc
	v_lshlrev_b32_e32 v36, 2, v4
	v_lshlrev_b32_e32 v4, 3, v20
	v_lshl_add_u64 v[4:5], s[78:79], 0, v[4:5]
	v_lshl_add_u64 v[24:25], v[4:5], 0, s[4:5]
	s_mov_b32 s4, s2
	s_branch .LBB0_163

.Lcv3_ret:
	s_cmp_eq_u32 s101, 6
	s_cbranch_scc1 .Lcv3_done2
	s_cmp_eq_u32 s101, 5
	s_cbranch_scc1 .Lcv3_done
	v_readlane_b32 s2, v254, 19
	v_readlane_b32 s87, v255, 4
	s_sub_i32 s2, s2, 77
	s_lshl_b32 s2, s2, 3
	s_add_i32 s2, s2, s87
	s_addk_i32 s2, 0x3800
	s_movk_i32 s43, 0x598
	s_movk_i32 s100, 0x3fff
	s_mov_b32 s101, 5
	s_mov_b32 s7, 0
	s_branch .Lcv_relay_fwd
.Lcv3_done:
	s_cmp_eq_u32 s101, 6
	s_cbranch_scc1 .Lcv3_done2
	v_readlane_b32 s2, v254, 19
	v_readlane_b32 s87, v255, 4
	s_sub_i32 s2, s2, 77
	s_lshl_b32 s2, s2, 3
	s_add_i32 s2, s2, s87
	s_addk_i32 s2, 0xe00
	s_movk_i32 s43, 0x598
	s_movk_i32 s100, 0xfff
	s_mov_b32 s101, 6
	s_mov_b32 s7, 0
	s_cmp_gt_i32 s2, s100
	s_cbranch_scc1 .Lcv3_done2
	s_branch .Lcv_relay_fwd

.Lcv2_ret:
	s_cmp_eq_u32 s101, 3
	s_cbranch_scc1 .Lcv2_done
	v_readlane_b32 s2, v254, 19
	v_readlane_b32 s87, v255, 4
	s_sub_i32 s2, s2, 32
	s_lshl_b32 s2, s2, 3
	s_add_i32 s2, s2, s87
	s_addk_i32 s2, 0x780
	s_movk_i32 s43, 0x700
	s_movk_i32 s100, 0xdff
	s_mov_b32 s101, 3
	s_mov_b32 s7, 0
	s_branch .Lcv_relay_fwd
